# attention: q/k/v tile loads carry the non-temporal hint (their producer stores are non-temporal)
# speedup vs baseline: 1.0104x; 1.0076x over previous
.LBB0_356:
	s_lshl_b32 s12, s12, 1
	s_waitcnt lgkmcnt(0)
	s_add_u32 s4, s4, s12
	v_ashrrev_i32_e32 v57, 31, v56
	v_add_u32_e32 v58, 32, v56
	s_addc_u32 s5, s5, 0
	v_lshlrev_b64 v[2:3], 10, v[56:57]
	v_lshl_add_u64 v[2:3], s[4:5], 0, v[2:3]
	v_ashrrev_i32_e32 v59, 31, v58
	v_lshl_add_u64 v[10:11], v[2:3], 0, v[124:125]
	v_lshlrev_b64 v[2:3], 10, v[58:59]
	v_lshl_add_u64 v[2:3], s[4:5], 0, v[2:3]
	v_lshl_add_u64 v[14:15], v[2:3], 0, v[124:125]
	v_mad_i64_i32 v[2:3], s[4:5], s6, v56, 0
	v_mad_i64_i32 v[4:5], s[4:5], s6, v58, 0
	v_lshl_add_u64 v[2:3], v[2:3], 1, s[0:1]
	v_lshl_add_u64 v[4:5], v[4:5], 1, s[0:1]
	v_lshl_add_u64 v[2:3], v[2:3], 0, v[124:125]
	v_lshl_add_u64 v[6:7], v[4:5], 0, v[124:125]
	global_load_dwordx4 v[2:5], v[2:3], off nt
	s_nop 0
	global_load_dwordx4 v[6:9], v[6:7], off nt
	s_nop 0
	global_load_dwordx4 v[10:13], v[10:11], off nt
	s_nop 0
	global_load_dwordx4 v[14:17], v[14:15], off nt
	s_movk_i32 s0, 0x48
	s_add_u32 s38, s31, s12
	v_ashrrev_i32_e32 v1, 2, v0
	v_bfe_u32 v25, v0, 4, 2
	v_mul_lo_u32 v18, v56, s0
	v_and_b32_e32 v20, 64, v162
	s_addc_u32 s39, s29, 0
	v_xor_b32_e32 v19, 16, v162
	v_bfi_b32 v61, -16, v1, v0
	v_lshlrev_b64 v[62:63], 9, v[56:57]
	v_lshlrev_b32_e32 v57, 1, v18
	v_lshlrev_b32_e32 v60, 4, v25
	v_add_u32_e32 v18, 64, v20
	s_movk_i32 s61, 0x90
	s_add_u32 s24, s27, s30
	v_and_b32_e32 v24, 15, v0
	v_and_b32_e32 v26, -16, v1
	v_mad_u64_u32 v[0:1], s[0:1], v61, s61, v[60:61]
	v_cmp_lt_i32_e32 vcc, v19, v18
	s_addc_u32 s27, s28, s79
	s_lshl_b64 s[28:29], s[20:21], 1
	v_xor_b32_e32 v21, 32, v162
	v_lshlrev_b32_e32 v67, 2, v25
	v_med3_i32 v20, v61, 8, 56
	v_cndmask_b32_e32 v1, v162, v19, vcc
	s_add_u32 s56, s24, s28
	v_cmp_lt_i32_e32 vcc, v21, v18
	v_or_b32_e32 v80, 16, v67
	v_add_u32_e32 v27, -8, v20
	v_lshlrev_b32_e32 v66, 2, v1
	v_add_u32_e32 v1, 8, v20
	s_addc_u32 s57, s27, s29
	v_cndmask_b32_e32 v18, v162, v21, vcc
	v_cmp_ge_u32_e32 vcc, v80, v27
	v_cmp_lt_u32_e64 s[0:1], v80, v1
	s_add_u32 s21, s25, s12
	v_or_b32_e32 v81, 18, v67
	s_addc_u32 s71, s26, 0
	s_and_b64 s[36:37], vcc, s[0:1]
	v_cmp_ge_u32_e32 vcc, v81, v27
	v_cmp_lt_u32_e64 s[0:1], v81, v1
	v_or_b32_e32 v79, 19, v67
	s_and_b64 s[30:31], vcc, s[0:1]
	v_cmp_ge_u32_e32 vcc, v79, v27
	v_cmp_lt_u32_e64 s[0:1], v79, v1
	v_or_b32_e32 v77, 32, v67
	s_and_b64 s[28:29], vcc, s[0:1]
	v_cmp_ge_u32_e32 vcc, v77, v27
	v_cmp_lt_u32_e64 s[0:1], v77, v1
	v_or_b32_e32 v76, 33, v67
	v_or_b32_e32 v78, 17, v67
	s_and_b64 s[26:27], vcc, s[0:1]
	v_cmp_ge_u32_e32 vcc, v76, v27
	v_cmp_lt_u32_e64 s[0:1], v76, v1
	v_or_b32_e32 v75, 34, v67
	v_cmp_ge_u32_e64 s[4:5], v78, v27
	v_cmp_lt_u32_e64 s[6:7], v78, v1
	s_and_b64 s[24:25], vcc, s[0:1]
	v_cmp_ge_u32_e32 vcc, v75, v27
	v_cmp_lt_u32_e64 s[0:1], v75, v1
	v_or_b32_e32 v74, 35, v67
	v_add_u32_e32 v22, v57, v124
	s_and_b64 s[34:35], s[4:5], s[6:7]
	s_and_b64 s[6:7], vcc, s[0:1]
	v_cmp_ge_u32_e32 vcc, v74, v27
	v_cmp_lt_u32_e64 s[0:1], v74, v1
	v_or_b32_e32 v73, 48, v67
	v_or_b32_e32 v72, 49, v67
	v_or_b32_e32 v71, 50, v67
	v_or_b32_e32 v70, 51, v67
	v_lshlrev_b64 v[64:65], 9, v[58:59]
	v_lshlrev_b32_e32 v59, 2, v18
	s_waitcnt vmcnt(3)
	ds_write_b128 v22, v[2:5] offset:18432
	s_waitcnt vmcnt(2)
	ds_write_b128 v22, v[6:9] offset:23040
	s_waitcnt vmcnt(1)
	ds_write_b128 v22, v[10:13] offset:9216
	s_waitcnt vmcnt(0)
	ds_write_b128 v22, v[14:17] offset:13824
	s_waitcnt lgkmcnt(0)
	s_barrier
	ds_read_b128 v[20:23], v0
	ds_read_b128 v[16:19], v0 offset:64
	s_and_b64 s[4:5], vcc, s[0:1]
	v_cmp_lt_u32_e64 s[46:47], v73, v1
	v_cmp_lt_u32_e64 s[44:45], v72, v1
	v_cmp_lt_u32_e64 s[42:43], v71, v1
	v_cmp_lt_u32_e64 s[0:1], v70, v1
	v_lshlrev_b32_e32 v0, 3, v25
	v_sub_u32_e32 v1, v67, v24
	v_mad_u32_u24 v85, v24, s61, v60
	v_mad_u32_u24 v86, v24, s61, v0
	v_lshlrev_b32_e32 v0, 6, v69
	s_movk_i32 s61, 0x7c
	v_sub_u32_e32 v1, v1, v26
	v_add_u32_e32 v87, 0xffffff40, v0
	v_mul_lo_u32 v0, v69, s61
	v_med3_i32 v2, v1, -15, 15
	v_lshl_add_u32 v2, v2, 2, v0
	s_mul_i32 s61, s70, 0x7c
	v_subrev_u32_e32 v2, s61, v2
	v_add_u32_e32 v88, 0xb5b0, v2
	v_add_u32_e32 v2, 1, v1
	v_med3_i32 v2, v2, -15, 15
	v_lshl_add_u32 v2, v2, 2, v0
	v_subrev_u32_e32 v2, s61, v2
	v_add_u32_e32 v89, 0xb5b0, v2
	v_add_u32_e32 v2, 2, v1
	v_med3_i32 v2, v2, -15, 15
	v_lshl_add_u32 v2, v2, 2, v0
	v_subrev_u32_e32 v2, s61, v2
	v_add_u32_e32 v90, 0xb5b0, v2
	v_add_u32_e32 v2, 3, v1
	v_med3_i32 v2, v2, -15, 15
	v_lshl_add_u32 v2, v2, 2, v0
	v_subrev_u32_e32 v2, s61, v2
	v_add_u32_e32 v91, 0xb5b0, v2
	v_add_u32_e32 v2, 16, v1
	v_med3_i32 v2, v2, -15, 15
	v_lshl_add_u32 v2, v2, 2, v0
	v_subrev_u32_e32 v2, s61, v2
	v_add_u32_e32 v92, 0xb5b0, v2
	v_add_u32_e32 v2, 17, v1
	v_med3_i32 v2, v2, -15, 15
	v_lshl_add_u32 v2, v2, 2, v0
	v_subrev_u32_e32 v2, s61, v2
	v_add_u32_e32 v93, 0xb5b0, v2
	v_add_u32_e32 v2, 18, v1
	v_med3_i32 v2, v2, -15, 15
	v_lshl_add_u32 v2, v2, 2, v0
	v_subrev_u32_e32 v2, s61, v2
	v_add_u32_e32 v94, 0xb5b0, v2
	v_add_u32_e32 v2, 19, v1
	v_med3_i32 v2, v2, -15, 15
	v_lshl_add_u32 v2, v2, 2, v0
	v_subrev_u32_e32 v2, s61, v2
	v_add_u32_e32 v95, 0xb5b0, v2
	v_add_u32_e32 v2, 32, v1
	v_med3_i32 v2, v2, -15, 15
	v_lshl_add_u32 v2, v2, 2, v0
	v_subrev_u32_e32 v2, s61, v2
	v_add_u32_e32 v96, 0xb5b0, v2
	v_add_u32_e32 v2, 33, v1
	v_med3_i32 v2, v2, -15, 15
	v_lshl_add_u32 v2, v2, 2, v0
	v_subrev_u32_e32 v2, s61, v2
	v_add_u32_e32 v97, 0xb5b0, v2
	v_add_u32_e32 v2, 34, v1
	v_med3_i32 v2, v2, -15, 15
	v_lshl_add_u32 v2, v2, 2, v0
	v_subrev_u32_e32 v2, s61, v2
	v_add_u32_e32 v98, 0xb5b0, v2
	v_add_u32_e32 v2, 35, v1
	v_med3_i32 v2, v2, -15, 15
	v_lshl_add_u32 v2, v2, 2, v0
	v_subrev_u32_e32 v2, s61, v2
	v_add_u32_e32 v99, 0xb5b0, v2
	v_add_u32_e32 v2, 48, v1
	v_med3_i32 v2, v2, -15, 15
	v_lshl_add_u32 v2, v2, 2, v0
	v_subrev_u32_e32 v2, s61, v2
	v_add_u32_e32 v100, 0xb5b0, v2
	v_add_u32_e32 v2, 49, v1
	v_med3_i32 v2, v2, -15, 15
	v_lshl_add_u32 v2, v2, 2, v0
	s_mul_i32 s72, s62, 0x7c
	v_subrev_u32_e32 v2, s61, v2
	s_addk_i32 s72, 0x7c
	v_add_u32_e32 v101, 0xb5b0, v2
	v_add_u32_e32 v2, 50, v1
	v_add_u32_e32 v1, 51, v1
	s_add_u32 s58, s10, s58
	v_med3_i32 v2, v2, -15, 15
	v_med3_i32 v1, v1, -15, 15
	s_addc_u32 s59, s11, s59
	v_lshl_add_u32 v2, v2, 2, v0
	v_lshl_add_u32 v0, v1, 2, v0
	v_or_b32_e32 v84, 1, v67
	v_or_b32_e32 v83, 2, v67
	v_or_b32_e32 v82, 3, v67
	s_add_u32 s58, s58, 0x4bb6080
	v_subrev_u32_e32 v2, s61, v2
	v_subrev_u32_e32 v0, s61, v0
	v_mov_b32_e32 v104, 0
	s_mov_b32 s13, 0
	v_mul_u32_u24_e32 v68, 0x90, v24
	v_cmp_ge_u32_e64 s[54:55], v67, v27
	v_cmp_ge_u32_e64 s[52:53], v84, v27
	v_cmp_ge_u32_e64 s[50:51], v83, v27
	v_cmp_ge_u32_e64 s[48:49], v82, v27
	s_addc_u32 s59, s59, 0
	s_add_i32 s60, s60, 64
	v_add_u32_e32 v102, 0xb5b0, v2
	v_add_u32_e32 v103, 0xb5b0, v0
	v_mov_b32_e32 v105, 0xf149f2ca
	s_mov_b32 s74, s20
	s_mov_b32 s75, 0
	v_mov_b32_e32 v8, 0
	v_mov_b32_e32 v9, v104
	v_mov_b32_e32 v10, v104
	v_mov_b32_e32 v11, v104
	v_mov_b32_e32 v12, 0
	v_mov_b32_e32 v13, v104
	v_mov_b32_e32 v14, v104
	v_mov_b32_e32 v15, v104
	v_mov_b32_e32 v4, 0
	v_mov_b32_e32 v5, v104
	v_mov_b32_e32 v6, v104
	v_mov_b32_e32 v7, v104
	v_mov_b32_e32 v0, 0
	v_mov_b32_e32 v1, v104
	v_mov_b32_e32 v2, v104
	v_mov_b32_e32 v3, v104

.LBB0_365:
	v_mad_i64_i32 v[34:35], s[64:65], s62, v56, 0
	v_mad_i64_i32 v[36:37], s[62:63], s62, v58, 0
	v_lshl_add_u64 v[26:27], v[62:63], 1, v[24:25]
	v_lshl_add_u64 v[24:25], v[64:65], 1, v[24:25]
	v_lshl_add_u64 v[34:35], v[34:35], 1, v[32:33]
	v_lshl_add_u64 v[32:33], v[36:37], 1, v[32:33]
	v_lshl_add_u64 v[26:27], v[26:27], 0, v[124:125]
	v_lshl_add_u64 v[28:29], v[24:25], 0, v[124:125]
	v_lshl_add_u64 v[34:35], v[34:35], 0, v[124:125]
	v_lshl_add_u64 v[36:37], v[32:33], 0, v[124:125]
	global_load_dwordx4 v[24:27], v[26:27], off nt
	s_nop 0
	global_load_dwordx4 v[28:31], v[28:29], off nt
	s_nop 0
	global_load_dwordx4 v[32:35], v[34:35], off nt
	s_nop 0
	global_load_dwordx4 v[36:39], v[36:37], off nt
	s_and_b32 s61, s75, 1
	s_mul_i32 s64, s61, 0x2400
	v_lshl_add_u32 v110, s64, 1, v85
	ds_read_b128 v[40:43], v110 offset:9216
	ds_read_b128 v[44:47], v110 offset:9280
	s_waitcnt lgkmcnt(1)
	v_mfma_f32_16x16x32_bf16 v[40:43], v[40:43], v[20:23], 0
	ds_read_b128 v[48:51], v110 offset:11520
	ds_read_b128 v[106:109], v110 offset:13824
	s_cmp_gt_u32 s75, 3
	s_waitcnt lgkmcnt(2)
	v_mfma_f32_16x16x32_bf16 v[52:55], v[44:47], v[16:19], v[40:43]
	s_cselect_b64 s[62:63], -1, 0
	s_and_b64 s[62:63], s[14:15], s[62:63]
	s_andn2_b64 vcc, exec, s[62:63]
	ds_read_b128 v[40:43], v110 offset:11584
	s_waitcnt lgkmcnt(2)
	v_mfma_f32_16x16x32_bf16 v[44:47], v[48:51], v[20:23], 0
	s_waitcnt lgkmcnt(0)
	v_mfma_f32_16x16x32_bf16 v[48:51], v[40:43], v[16:19], v[44:47]
	ds_read_b128 v[40:43], v110 offset:13888
	v_mfma_f32_16x16x32_bf16 v[44:47], v[106:109], v[20:23], 0
	ds_read_b128 v[106:109], v110 offset:16128
	s_waitcnt lgkmcnt(1)
	v_mfma_f32_16x16x32_bf16 v[44:47], v[40:43], v[16:19], v[44:47]
	ds_read_b128 v[40:43], v110 offset:16192
	s_waitcnt lgkmcnt(1)
	v_mfma_f32_16x16x32_bf16 v[106:109], v[106:109], v[20:23], 0
	s_waitcnt lgkmcnt(0)
	v_mfma_f32_16x16x32_bf16 v[40:43], v[40:43], v[16:19], v[106:109]
	s_cbranch_vccnz .LBB0_399
	s_nop 4
	v_mov_b32_e32 v108, 0xf149f2ca
	v_mov_b32_e32 v113, 0xf149f2ca
	s_and_saveexec_b64 s[62:63], s[54:55]
	s_cbranch_execz .LBB0_368
	v_add_u32_e32 v106, s13, v88
	ds_read_b32 v106, v106
	s_waitcnt lgkmcnt(0)
	v_add_f32_e32 v113, v52, v106

.LBB0_406:
	v_add_u32_e32 v26, s20, v26
	v_ashrrev_i32_e32 v27, 31, v26
	v_lshlrev_b64 v[26:27], 10, v[26:27]
	v_lshlrev_b64 v[24:25], 1, v[24:25]
	v_lshl_add_u64 v[26:27], s[38:39], 0, v[26:27]
	v_lshl_add_u64 v[32:33], s[56:57], 0, v[24:25]
	s_movk_i32 s13, 0x3000
	v_lshl_add_u64 v[24:25], v[62:63], 1, v[26:27]
	v_lshl_add_u64 v[26:27], v[64:65], 1, v[26:27]
	v_mad_i64_i32 v[34:35], s[20:21], v56, s13, v[32:33]
	v_mad_i64_i32 v[32:33], s[20:21], v58, s13, v[32:33]
	v_lshl_add_u64 v[24:25], v[24:25], 0, v[124:125]
	v_lshl_add_u64 v[28:29], v[26:27], 0, v[124:125]
	v_lshl_add_u64 v[34:35], v[34:35], 0, v[124:125]
	v_lshl_add_u64 v[36:37], v[32:33], 0, v[124:125]
	global_load_dwordx4 v[24:27], v[24:25], off nt
	s_nop 0
	global_load_dwordx4 v[28:31], v[28:29], off nt
	s_nop 0
	global_load_dwordx4 v[32:35], v[34:35], off nt
	s_nop 0
	global_load_dwordx4 v[36:39], v[36:37], off nt
	s_and_b32 s13, s73, 1
	s_mul_i32 s20, s13, 0x2400
	v_lshl_or_b32 v40, s20, 1, v60
	v_add_u32_e32 v54, v40, v68
	ds_read_b128 v[40:43], v54 offset:9216
	ds_read_b128 v[44:47], v54 offset:9280
	s_waitcnt lgkmcnt(1)
	v_mfma_f32_16x16x32_bf16 v[40:43], v[40:43], v[20:23], 0
	ds_read_b128 v[62:65], v54 offset:11520
	ds_read_b128 v[86:89], v54 offset:16128
	s_movk_i32 s56, 0x3000
	s_waitcnt lgkmcnt(2)
	v_mfma_f32_16x16x32_bf16 v[48:51], v[44:47], v[16:19], v[40:43]
	s_andn2_b64 vcc, exec, s[14:15]
	s_nop 1
	ds_read_b128 v[40:43], v54 offset:11584
	s_waitcnt lgkmcnt(2)
	v_mfma_f32_16x16x32_bf16 v[44:47], v[62:65], v[20:23], 0
	ds_read_b128 v[62:65], v54 offset:13824
	s_waitcnt lgkmcnt(1)
	v_mfma_f32_16x16x32_bf16 v[44:47], v[40:43], v[16:19], v[44:47]
	ds_read_b128 v[40:43], v54 offset:13888
	s_waitcnt lgkmcnt(1)
	v_mfma_f32_16x16x32_bf16 v[62:65], v[62:65], v[20:23], 0
	s_waitcnt lgkmcnt(0)
	v_mfma_f32_16x16x32_bf16 v[40:43], v[40:43], v[16:19], v[62:65]
	s_nop 5
	ds_read_b128 v[62:65], v54 offset:16192
	v_mfma_f32_16x16x32_bf16 v[20:23], v[86:89], v[20:23], 0
	s_waitcnt lgkmcnt(0)
	v_mfma_f32_16x16x32_bf16 v[16:19], v[62:65], v[16:19], v[20:23]
	s_cbranch_vccnz .LBB0_439
	s_nop 4
	v_subrev_u32_e32 v20, s70, v69
	v_add_u32_e32 v20, s73, v20
	s_movk_i32 s14, 0x7c
	v_mul_lo_u32 v20, v20, s14
	v_add_u32_e32 v85, 0xfffffe10, v20
	v_mov_b32_e32 v21, 0xf149f2ca
	v_mov_b32_e32 v55, 0xf149f2ca
	s_and_saveexec_b64 s[14:15], s[54:55]
	s_cbranch_execz .LBB0_409
	v_sub_u32_e32 v20, v67, v61
	v_med3_i32 v20, v20, -15, 15
	v_lshl_add_u32 v20, v20, 2, v85
	ds_read_b32 v20, v20 offset:47008
	s_waitcnt lgkmcnt(0)
	v_add_f32_e32 v55, v48, v20
